# peel_plus_attn_maxtrim
# baseline (speedup 1.0000x reference)
.LBB0_360:
	s_waitcnt lgkmcnt(7)
	v_mfma_f32_32x32x16_bf16 v[144:159], v[220:223], v[188:191], v[80:95]
	v_add_f32_e32 v2, v112, v113
	v_add_f32_e32 v2, v114, v2
	v_add_f32_e32 v2, v115, v2
	s_lshl_b32 s2, s2, 1
	v_add_f32_e32 v2, v116, v2
	v_add_u32_e32 v0, s2, v225
	v_add_f32_e32 v2, v117, v2
	v_cvt_pk_bf16_f32 v180, v112, v113
	v_cvt_pk_bf16_f32 v181, v114, v115
	s_waitcnt lgkmcnt(6)
	v_mfma_f32_32x32x16_bf16 v[128:143], v[216:219], v[188:191], v[80:95]
	v_add_f32_e32 v2, v118, v2
	v_add_f32_e32 v2, v119, v2
	v_add_f32_e32 v2, v120, v2
	v_add_f32_e32 v2, v121, v2
	v_cvt_pk_bf16_f32 v182, v116, v117
	v_cvt_pk_bf16_f32 v183, v118, v119
	s_waitcnt lgkmcnt(5)
	v_mfma_f32_32x32x16_bf16 v[144:159], v[212:215], v[184:187], v[144:159]
	v_add_f32_e32 v2, v122, v2
	v_add_f32_e32 v2, v123, v2
	v_add_f32_e32 v2, v124, v2
	v_add_f32_e32 v2, v125, v2
	v_cvt_pk_bf16_f32 v172, v120, v121
	v_cvt_pk_bf16_f32 v173, v122, v123
	s_waitcnt lgkmcnt(4)
	v_mfma_f32_32x32x16_bf16 v[128:143], v[208:211], v[184:187], v[128:143]
	v_add_f32_e32 v2, v126, v2
	v_add_f32_e32 v2, v127, v2
	v_add_f32_e32 v2, v96, v2
	v_add_f32_e32 v2, v97, v2
	v_cvt_pk_bf16_f32 v174, v124, v125
	v_cvt_pk_bf16_f32 v175, v126, v127
	s_waitcnt lgkmcnt(3)
	v_mfma_f32_32x32x16_bf16 v[144:159], v[204:207], v[176:179], v[144:159]
	v_add_f32_e32 v2, v98, v2
	v_add_f32_e32 v2, v99, v2
	v_add_f32_e32 v2, v100, v2
	v_add_f32_e32 v2, v101, v2
	v_cvt_pk_bf16_f32 v164, v96, v97
	v_cvt_pk_bf16_f32 v165, v98, v99
	s_waitcnt lgkmcnt(2)
	v_mfma_f32_32x32x16_bf16 v[128:143], v[200:203], v[176:179], v[128:143]
	v_add_f32_e32 v2, v102, v2
	v_add_f32_e32 v2, v103, v2
	v_add_f32_e32 v2, v104, v2
	v_add_f32_e32 v2, v105, v2
	v_cvt_pk_bf16_f32 v166, v100, v101
	v_cvt_pk_bf16_f32 v167, v102, v103
	s_waitcnt lgkmcnt(1)
	v_mfma_f32_32x32x16_bf16 v[144:159], v[196:199], v[168:171], v[144:159]
	v_add_f32_e32 v2, v106, v2
	v_add_f32_e32 v2, v107, v2
	v_add_f32_e32 v2, v108, v2
	v_add_f32_e32 v2, v109, v2
	v_cvt_pk_bf16_f32 v160, v104, v105
	v_cvt_pk_bf16_f32 v161, v106, v107
	s_waitcnt lgkmcnt(0)
	v_mfma_f32_32x32x16_bf16 v[128:143], v[192:195], v[168:171], v[128:143]
	v_add_f32_e32 v2, v110, v2
	v_add_f32_e32 v2, v111, v2
	v_add_f32_e32 v118, 0, v2
	v_cvt_pk_bf16_f32 v162, v108, v109
	v_cvt_pk_bf16_f32 v163, v110, v111
	ds_read_b64_tr_b16 v[112:113], v0 offset:24576
	ds_read_b64_tr_b16 v[114:115], v0 offset:25088
	ds_read_b64_tr_b16 v[96:97], v0 offset:28672
	ds_read_b64_tr_b16 v[98:99], v0 offset:29184
	ds_read_b64_tr_b16 v[10:11], v0 offset:25600
	ds_read_b64_tr_b16 v[12:13], v0 offset:26112
	ds_read_b64_tr_b16 v[6:7], v0 offset:29696
	ds_read_b64_tr_b16 v[8:9], v0 offset:30208
	ds_read_b64_tr_b16 v[2:3], v0 offset:26624
	ds_read_b64_tr_b16 v[4:5], v0 offset:27136
	ds_read_b64_tr_b16 v[108:109], v0 offset:30720
	ds_read_b64_tr_b16 v[110:111], v0 offset:31232
	ds_read_b64_tr_b16 v[104:105], v0 offset:27648
	ds_read_b64_tr_b16 v[106:107], v0 offset:28160
	ds_read_b64_tr_b16 v[100:101], v0 offset:31744
	ds_read_b64_tr_b16 v[102:103], v0 offset:32256
	v_lshl_add_u64 v[208:209], v[232:233], 0, s[4:5]
	v_lshl_add_u64 v[14:15], v[208:209], 0, s[76:77]
	s_add_i32 s2, s10, s84
	s_mov_b32 s3, m0
	s_mov_b32 m0, s2
	s_nop 0
	global_load_lds_dwordx4 v[14:15], off
	s_mov_b32 m0, s3
	v_lshl_add_u64 v[14:15], v[236:237], 0, s[4:5]
	v_lshl_add_u64 v[116:117], v[14:15], 0, s[98:99]
	s_lshl_b32 s2, s8, 1
	s_add_i32 s2, s2, s82
	s_mov_b32 s3, m0
	s_mov_b32 m0, s2
	s_nop 0
	global_load_lds_dwordx4 v[116:117], off
	s_mov_b32 m0, s3
	v_lshl_add_u64 v[116:117], v[14:15], 0, s[92:93]
	s_addk_i32 s2, 0x2000
	s_mov_b32 s3, m0
	s_mov_b32 m0, s2
	s_nop 0
	global_load_lds_dwordx4 v[116:117], off
	s_mov_b32 m0, s3
	v_max_f32_e32 v116, v144, v145
	v_max3_f32 v117, v146, v147, v129
	v_max3_f32 v116, v116, v128, v130
	v_max3_f32 v116, v116, v131, v148
	v_max3_f32 v117, v117, v150, v151
	v_max3_f32 v116, v116, v149, v132
	v_max3_f32 v117, v117, v134, v135
	v_max3_f32 v116, v116, v133, v152
	v_max3_f32 v117, v117, v154, v155
	v_max3_f32 v116, v116, v153, v136
	v_max3_f32 v117, v117, v138, v139
	v_max3_f32 v116, v116, v137, v156
	v_max3_f32 v117, v117, v158, v159
	v_max3_f32 v116, v116, v157, v140
	v_max3_f32 v117, v117, v142, v143
	v_max3_f32 v116, v116, v141, v117
	v_mov_b32_e32 v117, v116
	s_nop 1
	v_permlane32_swap_b32_e32 v116, v117
	v_max_f32_e32 v116, v116, v117
	v_cmp_lt_f32_e32 vcc, s67, v116
	s_cmp_lg_u64 vcc, 0
	v_add_f32_e32 v210, v227, v118
	s_cselect_b64 s[2:3], -1, 0
	s_cbranch_vccnz .LBB0_368

.LBB0_363:
	s_add_i32 s2, s8, 0x2000
	s_cmpk_lg_i32 s8, 0x4000
	s_cselect_b32 s68, s2, 0
	v_mfma_f32_32x32x16_bf16 v[112:127], v[96:99], v[188:191], v[80:95]
	v_add_f32_e32 v100, v144, v145
	v_add_f32_e32 v100, v146, v100
	v_add_f32_e32 v100, v147, v100
	s_lshl_b32 s2, s10, 1
	v_add_f32_e32 v100, v148, v100
	v_add_u32_e32 v230, s2, v225
	v_add_f32_e32 v96, v149, v100
	v_cvt_pk_bf16_f32 v180, v144, v145
	v_cvt_pk_bf16_f32 v181, v146, v147
	s_nop 0
	v_add_f32_e32 v96, v150, v96
	v_add_f32_e32 v96, v151, v96
	v_add_f32_e32 v96, v152, v96
	v_add_f32_e32 v144, v153, v96
	v_mfma_f32_32x32x16_bf16 v[96:111], v[200:203], v[188:191], v[80:95]
	v_cvt_pk_bf16_f32 v182, v148, v149
	v_cvt_pk_bf16_f32 v183, v150, v151
	v_mfma_f32_32x32x16_bf16 v[112:127], v[204:207], v[184:187], v[112:127]
	v_add_f32_e32 v144, v154, v144
	v_add_f32_e32 v144, v155, v144
	v_add_f32_e32 v144, v156, v144
	v_add_f32_e32 v144, v157, v144
	v_cvt_pk_bf16_f32 v172, v152, v153
	v_cvt_pk_bf16_f32 v173, v154, v155
	v_mfma_f32_32x32x16_bf16 v[96:111], v[196:199], v[184:187], v[96:111]
	v_add_f32_e32 v144, v158, v144
	v_add_f32_e32 v144, v159, v144
	v_add_f32_e32 v144, v128, v144
	v_add_f32_e32 v144, v129, v144
	v_cvt_pk_bf16_f32 v174, v156, v157
	v_cvt_pk_bf16_f32 v175, v158, v159
	v_mfma_f32_32x32x16_bf16 v[112:127], v[192:195], v[176:179], v[112:127]
	v_add_f32_e32 v144, v130, v144
	v_add_f32_e32 v144, v131, v144
	v_add_f32_e32 v144, v132, v144
	v_add_f32_e32 v144, v133, v144
	v_cvt_pk_bf16_f32 v164, v128, v129
	v_cvt_pk_bf16_f32 v165, v130, v131
	v_mfma_f32_32x32x16_bf16 v[96:111], v[10:13], v[176:179], v[96:111]
	v_add_f32_e32 v10, v134, v144
	v_add_f32_e32 v10, v135, v10
	v_add_f32_e32 v10, v136, v10
	v_add_f32_e32 v10, v137, v10
	v_cvt_pk_bf16_f32 v166, v132, v133
	v_cvt_pk_bf16_f32 v167, v134, v135
	v_mfma_f32_32x32x16_bf16 v[112:127], v[6:9], v[168:171], v[112:127]
	v_add_f32_e32 v6, v138, v10
	v_add_f32_e32 v6, v139, v6
	v_add_f32_e32 v6, v140, v6
	v_add_f32_e32 v6, v141, v6
	v_cvt_pk_bf16_f32 v160, v136, v137
	v_cvt_pk_bf16_f32 v161, v138, v139
	v_mfma_f32_32x32x16_bf16 v[96:111], v[2:5], v[168:171], v[96:111]
	v_add_f32_e32 v2, v142, v6
	v_add_f32_e32 v2, v143, v2
	v_add_f32_e32 v150, 0, v2
	v_cvt_pk_bf16_f32 v162, v140, v141
	v_cvt_pk_bf16_f32 v163, v142, v143
	ds_read_b64_tr_b16 v[144:145], v230 offset:24576
	ds_read_b64_tr_b16 v[146:147], v230 offset:25088
	ds_read_b64_tr_b16 v[140:141], v230 offset:28672
	ds_read_b64_tr_b16 v[142:143], v230 offset:29184
	ds_read_b64_tr_b16 v[136:137], v230 offset:25600
	ds_read_b64_tr_b16 v[138:139], v230 offset:26112
	ds_read_b64_tr_b16 v[132:133], v230 offset:29696
	ds_read_b64_tr_b16 v[134:135], v230 offset:30208
	ds_read_b64_tr_b16 v[128:129], v230 offset:26624
	ds_read_b64_tr_b16 v[130:131], v230 offset:27136
	ds_read_b64_tr_b16 v[10:11], v230 offset:30720
	ds_read_b64_tr_b16 v[12:13], v230 offset:31232
	ds_read_b64_tr_b16 v[6:7], v230 offset:27648
	ds_read_b64_tr_b16 v[8:9], v230 offset:28160
	ds_read_b64_tr_b16 v[2:3], v230 offset:31744
	ds_read_b64_tr_b16 v[4:5], v230 offset:32256
	s_mov_b64 s[2:3], 0xa0000
	v_lshl_add_u64 v[148:149], v[208:209], 0, s[2:3]
	s_add_i32 s2, s8, s84
	s_mov_b32 s3, m0
	s_mov_b32 m0, s2
	s_nop 0
	global_load_lds_dwordx4 v[148:149], off
	s_mov_b32 m0, s3
	s_mov_b64 s[2:3], 0x24860000
	v_lshl_add_u64 v[148:149], v[14:15], 0, s[2:3]
	s_lshl_b32 s2, s68, 1
	s_add_i32 s6, s2, s82
	s_mov_b32 s2, m0
	s_mov_b32 m0, s6
	s_nop 0
	global_load_lds_dwordx4 v[148:149], off
	s_mov_b32 m0, s2
	s_mov_b64 s[2:3], 0x24860080
	v_lshl_add_u64 v[14:15], v[14:15], 0, s[2:3]
	s_add_i32 s2, s6, 0x2000
	s_mov_b32 s3, m0
	s_mov_b32 m0, s2
	s_nop 0
	global_load_lds_dwordx4 v[14:15], off
	s_mov_b32 m0, s3
	v_max_f32_e32 v14, v112, v113
	v_max3_f32 v15, v114, v115, v97
	v_max3_f32 v14, v14, v96, v98
	v_max3_f32 v14, v14, v99, v116
	v_max3_f32 v15, v15, v118, v119
	v_max3_f32 v14, v14, v117, v100
	v_max3_f32 v15, v15, v102, v103
	v_max3_f32 v14, v14, v101, v120
	v_max3_f32 v15, v15, v122, v123
	v_max3_f32 v14, v14, v121, v104
	v_max3_f32 v15, v15, v106, v107
	v_max3_f32 v14, v14, v105, v124
	v_max3_f32 v15, v15, v126, v127
	v_max3_f32 v14, v14, v125, v108
	v_max3_f32 v15, v15, v110, v111
	v_max3_f32 v14, v14, v109, v15
	v_mov_b32_e32 v15, v14
	s_nop 1
	v_permlane32_swap_b32_e32 v14, v15
	v_max_f32_e32 v14, v14, v15
	v_cmp_lt_f32_e32 vcc, s67, v14
	s_cmp_lg_u64 vcc, 0
	v_add_f32_e32 v227, v210, v150
	s_cselect_b64 s[2:3], -1, 0
	s_cbranch_vccnz .LBB0_371

.LBB0_384:
	v_add_f32_e32 v227, v227, v116
	v_max_f32_e32 v116, v144, v145
	v_max3_f32 v117, v146, v147, v129
	v_max3_f32 v116, v116, v128, v130
	v_max3_f32 v116, v116, v131, v148
	v_max3_f32 v117, v117, v150, v151
	v_max3_f32 v116, v116, v149, v132
	v_max3_f32 v117, v117, v134, v135
	v_max3_f32 v116, v116, v133, v152
	v_max3_f32 v117, v117, v154, v155
	v_max3_f32 v116, v116, v153, v136
	v_max3_f32 v117, v117, v138, v139
	v_max3_f32 v116, v116, v137, v156
	v_max3_f32 v117, v117, v158, v159
	v_max3_f32 v116, v116, v157, v140
	v_max3_f32 v117, v117, v142, v143
	v_max3_f32 v116, v116, v141, v117
	v_mov_b32_e32 v117, v116
	s_nop 1
	v_permlane32_swap_b32_e32 v116, v117
	v_max_f32_e32 v116, v116, v117
	v_cmp_lt_f32_e32 vcc, s67, v116
	s_cmp_lg_u64 vcc, 0
	s_cselect_b64 s[2:3], -1, 0
	s_cbranch_vccnz .LBB0_422

.LBB0_399:
	v_add_f32_e32 v227, v227, v148
	v_max_f32_e32 v148, v112, v113
	v_max3_f32 v149, v114, v115, v97
	v_max3_f32 v148, v148, v96, v98
	v_max3_f32 v148, v148, v99, v116
	v_max3_f32 v149, v149, v118, v119
	v_max3_f32 v148, v148, v117, v100
	v_max3_f32 v149, v149, v102, v103
	v_max3_f32 v148, v148, v101, v120
	v_max3_f32 v149, v149, v122, v123
	v_max3_f32 v148, v148, v121, v104
	v_max3_f32 v149, v149, v106, v107
	v_max3_f32 v148, v148, v105, v124
	v_max3_f32 v149, v149, v126, v127
	v_max3_f32 v148, v148, v125, v108
	v_max3_f32 v149, v149, v110, v111
	v_max3_f32 v148, v148, v109, v149
	v_mov_b32_e32 v149, v148
	s_nop 1
	v_permlane32_swap_b32_e32 v148, v149
	v_max_f32_e32 v148, v148, v149
	v_cmp_lt_f32_e32 vcc, s67, v148
	s_cmp_lg_u64 vcc, 0
	s_cselect_b64 s[6:7], -1, 0
	s_cbranch_vccnz .LBB0_425

.LBB0_429:
	v_add_f32_e32 v2, v112, v113
	v_add_f32_e32 v2, v114, v2
	v_add_f32_e32 v2, v115, v2
	v_add_f32_e32 v2, v116, v2
	v_add_u32_e32 v0, s94, v225
	v_add_f32_e32 v2, v117, v2
	v_cvt_pk_bf16_f32 v180, v112, v113
	v_cvt_pk_bf16_f32 v181, v114, v115
	s_waitcnt lgkmcnt(7)
	v_mfma_f32_32x32x16_bf16 v[128:143], v[220:223], v[188:191], v[80:95]
	s_waitcnt lgkmcnt(6)
	v_mfma_f32_32x32x16_bf16 v[80:95], v[216:219], v[188:191], v[80:95]
	v_add_f32_e32 v2, v118, v2
	v_add_f32_e32 v2, v119, v2
	v_add_f32_e32 v2, v120, v2
	v_add_f32_e32 v2, v121, v2
	v_cvt_pk_bf16_f32 v182, v116, v117
	v_cvt_pk_bf16_f32 v183, v118, v119
	s_nop 0
	v_add_f32_e32 v2, v122, v2
	v_add_f32_e32 v2, v123, v2
	v_add_f32_e32 v2, v124, v2
	v_add_f32_e32 v2, v125, v2
	v_cvt_pk_bf16_f32 v172, v120, v121
	v_cvt_pk_bf16_f32 v173, v122, v123
	s_waitcnt lgkmcnt(5)
	v_mfma_f32_32x32x16_bf16 v[128:143], v[212:215], v[184:187], v[128:143]
	s_waitcnt lgkmcnt(4)
	v_mfma_f32_32x32x16_bf16 v[80:95], v[208:211], v[184:187], v[80:95]
	v_add_f32_e32 v2, v126, v2
	v_add_f32_e32 v2, v127, v2
	v_add_f32_e32 v2, v96, v2
	v_add_f32_e32 v2, v97, v2
	v_cvt_pk_bf16_f32 v174, v124, v125
	v_cvt_pk_bf16_f32 v175, v126, v127
	s_nop 0
	v_add_f32_e32 v2, v98, v2
	v_add_f32_e32 v2, v99, v2
	v_add_f32_e32 v2, v100, v2
	v_add_f32_e32 v2, v101, v2
	v_cvt_pk_bf16_f32 v164, v96, v97
	v_cvt_pk_bf16_f32 v165, v98, v99
	s_waitcnt lgkmcnt(3)
	v_mfma_f32_32x32x16_bf16 v[128:143], v[204:207], v[176:179], v[128:143]
	s_waitcnt lgkmcnt(2)
	v_mfma_f32_32x32x16_bf16 v[80:95], v[200:203], v[176:179], v[80:95]
	v_add_f32_e32 v2, v102, v2
	v_add_f32_e32 v2, v103, v2
	v_add_f32_e32 v2, v104, v2
	v_add_f32_e32 v2, v105, v2
	v_cvt_pk_bf16_f32 v166, v100, v101
	v_cvt_pk_bf16_f32 v167, v102, v103
	s_nop 0
	v_add_f32_e32 v2, v106, v2
	v_add_f32_e32 v2, v107, v2
	v_add_f32_e32 v2, v108, v2
	v_add_f32_e32 v2, v109, v2
	v_cvt_pk_bf16_f32 v160, v104, v105
	v_cvt_pk_bf16_f32 v161, v106, v107
	s_waitcnt lgkmcnt(1)
	v_mfma_f32_32x32x16_bf16 v[128:143], v[196:199], v[168:171], v[128:143]
	s_waitcnt lgkmcnt(0)
	v_mfma_f32_32x32x16_bf16 v[80:95], v[192:195], v[168:171], v[80:95]
	v_add_f32_e32 v2, v110, v2
	v_add_f32_e32 v2, v111, v2
	v_add_f32_e32 v14, 0, v2
	v_cvt_pk_bf16_f32 v162, v108, v109
	v_cvt_pk_bf16_f32 v163, v110, v111
	ds_read_b64_tr_b16 v[168:169], v0 offset:24576
	ds_read_b64_tr_b16 v[170:171], v0 offset:25088
	ds_read_b64_tr_b16 v[156:157], v0 offset:28672
	ds_read_b64_tr_b16 v[158:159], v0 offset:29184
	ds_read_b64_tr_b16 v[152:153], v0 offset:25600
	ds_read_b64_tr_b16 v[154:155], v0 offset:26112
	ds_read_b64_tr_b16 v[148:149], v0 offset:29696
	ds_read_b64_tr_b16 v[150:151], v0 offset:30208
	ds_read_b64_tr_b16 v[144:145], v0 offset:26624
	ds_read_b64_tr_b16 v[146:147], v0 offset:27136
	ds_read_b64_tr_b16 v[10:11], v0 offset:30720
	ds_read_b64_tr_b16 v[12:13], v0 offset:31232
	ds_read_b64_tr_b16 v[6:7], v0 offset:27648
	ds_read_b64_tr_b16 v[8:9], v0 offset:28160
	ds_read_b64_tr_b16 v[2:3], v0 offset:31744
	ds_read_b64_tr_b16 v[4:5], v0 offset:32256
	v_sub_u32_e32 v15, v242, v250
	v_add_u32_e32 v15, 0xffffff40, v15
	v_add_f32_e32 v14, v227, v14
	v_cmp_gt_i32_e64 s[60:61], 26, v15
	v_cmp_gt_i32_e64 s[62:63], 27, v15
	v_cmp_gt_i32_e64 s[58:59], 25, v15
	s_and_b64 s[60:61], s[62:63], s[60:61]
	v_cmp_gt_i32_e64 s[56:57], 24, v15
	s_and_b64 s[58:59], s[60:61], s[58:59]
	v_cmp_gt_i32_e64 s[54:55], 19, v15
	s_and_b64 s[56:57], s[58:59], s[56:57]
	v_cmp_gt_i32_e64 s[52:53], 18, v15
	s_and_b64 s[54:55], s[56:57], s[54:55]
	v_cmp_gt_i32_e64 s[50:51], 17, v15
	s_and_b64 s[52:53], s[54:55], s[52:53]
	v_cmp_gt_i32_e64 s[48:49], 16, v15
	s_and_b64 s[50:51], s[52:53], s[50:51]
	v_cmp_gt_i32_e64 s[46:47], 11, v15
	s_and_b64 s[48:49], s[50:51], s[48:49]
	v_cmp_gt_i32_e64 s[44:45], 10, v15
	s_and_b64 s[46:47], s[48:49], s[46:47]
	v_cmp_gt_i32_e64 s[42:43], 9, v15
	s_and_b64 s[44:45], s[46:47], s[44:45]
	v_cmp_gt_i32_e64 s[40:41], 8, v15
	s_and_b64 s[42:43], s[44:45], s[42:43]
	v_cmp_gt_i32_e64 s[38:39], 3, v15
	s_and_b64 s[40:41], s[42:43], s[40:41]
	v_cmp_gt_i32_e64 s[36:37], 2, v15
	s_and_b64 s[38:39], s[40:41], s[38:39]
	v_cmp_gt_i32_e64 s[34:35], 1, v15
	s_and_b64 s[36:37], s[38:39], s[36:37]
	v_cmp_gt_i32_e64 s[30:31], 0, v15
	s_and_b64 s[34:35], s[36:37], s[34:35]
	s_and_b64 s[30:31], s[34:35], s[30:31]
	v_cmp_gt_i32_e64 s[26:27], 58, v15
	v_cndmask_b32_e64 v96, v128, v243, s[30:31]
	v_cmp_gt_i32_e64 s[30:31], 59, v15
	v_cmp_gt_i32_e64 s[24:25], 57, v15
	s_and_b64 s[26:27], s[30:31], s[26:27]
	v_cmp_gt_i32_e64 s[22:23], 56, v15
	s_and_b64 s[24:25], s[26:27], s[24:25]
	v_cmp_gt_i32_e64 s[20:21], 51, v15
	s_and_b64 s[22:23], s[24:25], s[22:23]
	v_cmp_gt_i32_e64 s[18:19], 50, v15
	s_and_b64 s[20:21], s[22:23], s[20:21]
	v_cmp_gt_i32_e64 s[16:17], 49, v15
	s_and_b64 s[18:19], s[20:21], s[18:19]
	v_cmp_gt_i32_e64 s[14:15], 48, v15
	s_and_b64 s[16:17], s[18:19], s[16:17]
	v_cmp_gt_i32_e64 s[12:13], 43, v15
	s_and_b64 s[14:15], s[16:17], s[14:15]
	v_cmp_gt_i32_e64 s[10:11], 42, v15
	s_and_b64 s[12:13], s[14:15], s[12:13]
	v_cmp_gt_i32_e64 s[8:9], 41, v15
	s_and_b64 s[10:11], s[12:13], s[10:11]
	v_cmp_gt_i32_e64 s[6:7], 40, v15
	s_and_b64 s[8:9], s[10:11], s[8:9]
	v_cmp_gt_i32_e64 s[4:5], 35, v15
	s_and_b64 s[6:7], s[8:9], s[6:7]
	v_cmp_gt_i32_e64 s[28:29], 34, v15
	s_and_b64 s[4:5], s[6:7], s[4:5]
	v_cmp_gt_i32_e64 s[0:1], 33, v15
	v_cndmask_b32_e64 v83, v83, v243, s[4:5]
	s_and_b64 s[4:5], s[4:5], s[28:29]
	v_cmp_gt_i32_e32 vcc, 32, v15
	v_cndmask_b32_e64 v97, v129, v243, s[34:35]
	s_and_b64 s[0:1], s[4:5], s[0:1]
	s_and_b64 vcc, s[0:1], vcc
	v_max_f32_e32 v15, v97, v97
	v_max_f32_e32 v112, v96, v96
	v_cndmask_b32_e64 v99, v131, v243, s[38:39]
	v_cndmask_b32_e64 v98, v130, v243, s[36:37]
	v_cndmask_b32_e64 v82, v82, v243, s[4:5]
	v_cndmask_b32_e64 v81, v81, v243, s[0:1]
	v_cndmask_b32_e32 v80, v80, v243, vcc
	v_max_f32_e32 v15, v112, v15
	v_cndmask_b32_e64 v103, v135, v243, s[46:47]
	v_cndmask_b32_e64 v102, v134, v243, s[44:45]
	v_cndmask_b32_e64 v100, v132, v243, s[40:41]
	v_max3_f32 v112, v98, v99, v81
	v_max3_f32 v15, v15, v80, v82
	v_cndmask_b32_e64 v101, v133, v243, s[42:43]
	v_cndmask_b32_e64 v87, v87, v243, s[12:13]
	v_cndmask_b32_e64 v86, v86, v243, s[10:11]
	v_cndmask_b32_e64 v84, v84, v243, s[6:7]
	v_max3_f32 v15, v15, v83, v100
	v_max3_f32 v112, v112, v102, v103
	v_cndmask_b32_e64 v107, v139, v243, s[54:55]
	v_cndmask_b32_e64 v106, v138, v243, s[52:53]
	v_cndmask_b32_e64 v104, v136, v243, s[48:49]
	v_cndmask_b32_e64 v85, v85, v243, s[8:9]
	v_max3_f32 v15, v15, v101, v84
	v_max3_f32 v112, v112, v86, v87
	v_cndmask_b32_e64 v105, v137, v243, s[50:51]
	v_cndmask_b32_e64 v91, v91, v243, s[20:21]
	v_cndmask_b32_e64 v90, v90, v243, s[18:19]
	v_cndmask_b32_e64 v88, v88, v243, s[14:15]
	v_max3_f32 v15, v15, v85, v104
	v_max3_f32 v112, v112, v106, v107
	v_cndmask_b32_e64 v111, v143, v243, s[62:63]
	v_cndmask_b32_e64 v110, v142, v243, s[60:61]
	v_cndmask_b32_e64 v108, v140, v243, s[56:57]
	v_cndmask_b32_e64 v89, v89, v243, s[16:17]
	v_max3_f32 v15, v15, v105, v88
	v_max3_f32 v112, v112, v90, v91
	v_cndmask_b32_e64 v109, v141, v243, s[58:59]
	v_cndmask_b32_e64 v95, v95, v243, s[30:31]
	v_cndmask_b32_e64 v94, v94, v243, s[26:27]
	v_cndmask_b32_e64 v92, v92, v243, s[22:23]
	v_max3_f32 v15, v15, v89, v108
	v_max3_f32 v112, v112, v110, v111
	v_cndmask_b32_e64 v93, v93, v243, s[24:25]
	v_max3_f32 v15, v15, v109, v92
	v_max3_f32 v112, v112, v94, v95
	v_max3_f32 v15, v15, v93, v112
	v_mov_b32_e32 v112, v15
	s_nop 1
	v_permlane32_swap_b32_e32 v15, v112
	v_max_f32_e32 v15, v15, v112
	v_cmp_lt_f32_e32 vcc, s67, v15
	s_cmp_lg_u64 vcc, 0
	s_cselect_b64 s[0:1], -1, 0
	s_cbranch_vccnz .LBB0_435
	s_mov_b32 s94, s83
